# stack9 with the streaming stores back to plain nt (no sc0 sc1 write-through)
# baseline (speedup 1.0000x reference)
; __device__ __forceinline__ unsigned pk2(float lo, float hi) { f32v2 v = {lo, hi}; bf16v2 r = __builtin_convertvector(v, bf16v2); return __builtin_bit_cast(unsigned, r); }
;     __device__ __forceinline__ void operator()(f32x4 (&acc)[2][2][4][2], const Unit& u, int wr, int wc, int fr, int fq) const {
;     ...
;         for (int ai = 0; ai < 2; ++ai)
; #pragma unroll
;             for (int m = 0; m < 4; ++m) {
;                 const size_t row = (size_t)(row0 + ai * HALF + m * 16);
; #pragma unroll
;                 for (int bj = 0; bj < 2; ++bj) {
;                     f32x4 v0 = acc[ai][bj][m][0], v1 = acc[ai][bj][m][1];
;                     const int cl = cl0 + bj * HALF;
;                     if constexpr (MODE == 0 || MODE == 1) {
;                         if (MODE == 1) {
; #pragma unroll
;                             for (int e = 0; e < 4; ++e) { const float a = fmaxf(v0[e], 0.f), b = fmaxf(v1[e], 0.f); v0[e] = a * a; v1[e] = b * b; }
;                         }
;                         u32x4 w; w.x = pk2(v0[0], v0[1]); w.y = pk2(v0[2], v0[3]); w.z = pk2(v1[0], v1[1]); w.w = pk2(v1[2], v1[3]);
;                         if constexpr (MODE == 1) __builtin_nontemporal_store(w, (u32x4*)(O + row * ldc + u.pn * BM + cl));
;                         else *(u32x4*)(O + row * ldc + u.pn * BM + cl) = w;
.LBB0_561:
	s_andn2_b64 vcc, exec, s[6:7]
	s_cbranch_vccnz .LBB0_563
	v_ashrrev_i32_e32 v147, 31, v146
	s_lshl_b32 s6, s70, 8
	v_lshlrev_b64 v[128:129], 13, v[146:147]
	v_max_f32_e32 v132, 0, v120
	v_max_f32_e32 v148, 0, v122
	s_ashr_i32 s7, s6, 31
	v_lshl_add_u64 v[128:129], s[92:93], 0, v[128:129]
	v_max_f32_e32 v130, 0, v124
	v_max_f32_e32 v131, 0, v125
	v_max_f32_e32 v133, 0, v121
	v_max_f32_e32 v134, 0, v126
	v_max_f32_e32 v135, 0, v127
	v_max_f32_e32 v149, 0, v123
	s_lshl_b64 s[6:7], s[6:7], 1
	v_pk_mul_f32 v[130:131], v[130:131], v[130:131]
	v_pk_mul_f32 v[132:133], v[132:133], v[132:133]
	v_pk_mul_f32 v[134:135], v[134:135], v[134:135]
	v_pk_mul_f32 v[148:149], v[148:149], v[148:149]
	v_lshl_add_u64 v[128:129], v[128:129], 0, s[6:7]
	v_lshlrev_b32_e32 v178, 1, v138
	v_cvt_pk_bf16_f32 v130, v130, v131
	v_cvt_pk_bf16_f32 v131, v134, v135
	v_cvt_pk_bf16_f32 v132, v132, v133
	v_cvt_pk_bf16_f32 v133, v148, v149
	v_lshl_add_u64 v[128:129], v[128:129], 0, v[178:179]
	global_store_dwordx4 v[128:129], v[130:133], off nt
	s_nop 1
	v_max_f32_e32 v132, 0, v112
	v_max_f32_e32 v148, 0, v114
	v_max_f32_e32 v130, 0, v116
	v_max_f32_e32 v131, 0, v117
	v_max_f32_e32 v133, 0, v113
	v_max_f32_e32 v134, 0, v118
	v_max_f32_e32 v135, 0, v119
	v_max_f32_e32 v149, 0, v115
	v_pk_mul_f32 v[130:131], v[130:131], v[130:131]
	v_pk_mul_f32 v[132:133], v[132:133], v[132:133]
	v_pk_mul_f32 v[134:135], v[134:135], v[134:135]
	v_pk_mul_f32 v[148:149], v[148:149], v[148:149]
	v_cvt_pk_bf16_f32 v130, v130, v131
	v_cvt_pk_bf16_f32 v131, v134, v135
	v_cvt_pk_bf16_f32 v132, v132, v133
	v_cvt_pk_bf16_f32 v133, v148, v149
	global_store_dwordx4 v[128:129], v[130:133], off offset:256 nt
	s_nop 1
	v_max_f32_e32 v148, 0, v110
	v_or_b32_e32 v130, 16, v146
	v_ashrrev_i32_e32 v131, 31, v130
	v_lshlrev_b64 v[130:131], 13, v[130:131]
	v_lshl_add_u64 v[134:135], s[92:93], 0, v[130:131]
	v_max_f32_e32 v150, 0, v106
	v_max_f32_e32 v132, 0, v104
	v_max_f32_e32 v149, 0, v111
	v_max_f32_e32 v130, 0, v108
	v_max_f32_e32 v131, 0, v109
	v_max_f32_e32 v133, 0, v105
	v_max_f32_e32 v151, 0, v107
	v_pk_mul_f32 v[130:131], v[130:131], v[130:131]
	v_pk_mul_f32 v[132:133], v[132:133], v[132:133]
	v_pk_mul_f32 v[148:149], v[148:149], v[148:149]
	v_pk_mul_f32 v[150:151], v[150:151], v[150:151]
	v_lshl_add_u64 v[134:135], v[134:135], 0, s[6:7]
	v_cvt_pk_bf16_f32 v130, v130, v131
	v_cvt_pk_bf16_f32 v131, v148, v149
	v_cvt_pk_bf16_f32 v132, v132, v133
	v_cvt_pk_bf16_f32 v133, v150, v151
	v_lshl_add_u64 v[134:135], v[134:135], 0, v[178:179]
	v_max_f32_e32 v148, 0, v102
	global_store_dwordx4 v[134:135], v[130:133], off nt
	s_nop 1
	v_max_f32_e32 v150, 0, v98
	v_max_f32_e32 v132, 0, v96
	v_max_f32_e32 v149, 0, v103
	v_max_f32_e32 v130, 0, v100
	v_max_f32_e32 v131, 0, v101
	v_max_f32_e32 v133, 0, v97
	v_max_f32_e32 v151, 0, v99
	v_pk_mul_f32 v[130:131], v[130:131], v[130:131]
	v_pk_mul_f32 v[132:133], v[132:133], v[132:133]
	v_pk_mul_f32 v[148:149], v[148:149], v[148:149]
	v_pk_mul_f32 v[150:151], v[150:151], v[150:151]
	v_cvt_pk_bf16_f32 v130, v130, v131
	v_cvt_pk_bf16_f32 v131, v148, v149
	v_cvt_pk_bf16_f32 v132, v132, v133
	v_cvt_pk_bf16_f32 v133, v150, v151
	global_store_dwordx4 v[134:135], v[130:133], off offset:256 nt
	s_nop 1
	v_max_f32_e32 v148, 0, v94
	v_or_b32_e32 v130, 32, v146
	v_ashrrev_i32_e32 v131, 31, v130
	v_lshlrev_b64 v[130:131], 13, v[130:131]
	v_lshl_add_u64 v[134:135], s[92:93], 0, v[130:131]
	v_max_f32_e32 v150, 0, v90
	v_max_f32_e32 v132, 0, v88
	v_max_f32_e32 v149, 0, v95
	v_max_f32_e32 v130, 0, v92
	v_max_f32_e32 v131, 0, v93
	v_max_f32_e32 v133, 0, v89
	v_max_f32_e32 v151, 0, v91
	v_pk_mul_f32 v[130:131], v[130:131], v[130:131]
	v_pk_mul_f32 v[132:133], v[132:133], v[132:133]
	v_pk_mul_f32 v[148:149], v[148:149], v[148:149]
	v_pk_mul_f32 v[150:151], v[150:151], v[150:151]
	v_lshl_add_u64 v[134:135], v[134:135], 0, s[6:7]
	v_cvt_pk_bf16_f32 v130, v130, v131
	v_cvt_pk_bf16_f32 v131, v148, v149
	v_cvt_pk_bf16_f32 v132, v132, v133
	v_cvt_pk_bf16_f32 v133, v150, v151
	v_lshl_add_u64 v[134:135], v[134:135], 0, v[178:179]
	v_max_f32_e32 v148, 0, v86
	global_store_dwordx4 v[134:135], v[130:133], off nt
	s_nop 1
	v_max_f32_e32 v150, 0, v82
	v_max_f32_e32 v132, 0, v80
	v_max_f32_e32 v149, 0, v87
	v_max_f32_e32 v130, 0, v84
	v_max_f32_e32 v131, 0, v85
	v_max_f32_e32 v133, 0, v81
	v_max_f32_e32 v151, 0, v83
	v_pk_mul_f32 v[130:131], v[130:131], v[130:131]
	v_pk_mul_f32 v[132:133], v[132:133], v[132:133]
	v_pk_mul_f32 v[148:149], v[148:149], v[148:149]
	v_pk_mul_f32 v[150:151], v[150:151], v[150:151]
	v_cvt_pk_bf16_f32 v130, v130, v131
	v_cvt_pk_bf16_f32 v131, v148, v149
	v_cvt_pk_bf16_f32 v132, v132, v133
	v_cvt_pk_bf16_f32 v133, v150, v151
	global_store_dwordx4 v[134:135], v[130:133], off offset:256 nt
	s_nop 1
	v_max_f32_e32 v148, 0, v78
	v_or_b32_e32 v130, 48, v146
	v_ashrrev_i32_e32 v131, 31, v130
	v_lshlrev_b64 v[130:131], 13, v[130:131]
	v_lshl_add_u64 v[134:135], s[92:93], 0, v[130:131]
	v_max_f32_e32 v150, 0, v74
	v_max_f32_e32 v132, 0, v72
	v_max_f32_e32 v149, 0, v79
	v_max_f32_e32 v130, 0, v76
	v_max_f32_e32 v131, 0, v77
	v_max_f32_e32 v133, 0, v73
	v_max_f32_e32 v151, 0, v75
	v_pk_mul_f32 v[130:131], v[130:131], v[130:131]
	v_pk_mul_f32 v[132:133], v[132:133], v[132:133]
	v_pk_mul_f32 v[148:149], v[148:149], v[148:149]
	v_pk_mul_f32 v[150:151], v[150:151], v[150:151]
	v_lshl_add_u64 v[134:135], v[134:135], 0, s[6:7]
	v_cvt_pk_bf16_f32 v130, v130, v131
	v_cvt_pk_bf16_f32 v131, v148, v149
	v_cvt_pk_bf16_f32 v132, v132, v133
	v_cvt_pk_bf16_f32 v133, v150, v151
	v_lshl_add_u64 v[134:135], v[134:135], 0, v[178:179]
	v_max_f32_e32 v148, 0, v70
	global_store_dwordx4 v[134:135], v[130:133], off nt
; __device__ __forceinline__ unsigned pk2(float lo, float hi) { f32v2 v = {lo, hi}; bf16v2 r = __builtin_convertvector(v, bf16v2); return __builtin_bit_cast(unsigned, r); }
;     __device__ __forceinline__ void operator()(f32x4 (&acc)[2][2][4][2], const Unit& u, int wr, int wc, int fr, int fq) const {
;     ...
;         for (int ai = 0; ai < 2; ++ai)
; #pragma unroll
;             for (int m = 0; m < 4; ++m) {
;                 const size_t row = (size_t)(row0 + ai * HALF + m * 16);
; #pragma unroll
;                 for (int bj = 0; bj < 2; ++bj) {
;                     f32x4 v0 = acc[ai][bj][m][0], v1 = acc[ai][bj][m][1];
;                     const int cl = cl0 + bj * HALF;
;                     if constexpr (MODE == 0 || MODE == 1) {
;                         if (MODE == 1) {
; #pragma unroll
;                             for (int e = 0; e < 4; ++e) { const float a = fmaxf(v0[e], 0.f), b = fmaxf(v1[e], 0.f); v0[e] = a * a; v1[e] = b * b; }
;                         }
;                         u32x4 w; w.x = pk2(v0[0], v0[1]); w.y = pk2(v0[2], v0[3]); w.z = pk2(v1[0], v1[1]); w.w = pk2(v1[2], v1[3]);
;                         if constexpr (MODE == 1) __builtin_nontemporal_store(w, (u32x4*)(O + row * ldc + u.pn * BM + cl));
;                         else *(u32x4*)(O + row * ldc + u.pn * BM + cl) = w;
	s_nop 1
	v_max_f32_e32 v150, 0, v66
	v_max_f32_e32 v132, 0, v64
	v_max_f32_e32 v149, 0, v71
	v_max_f32_e32 v130, 0, v68
	v_max_f32_e32 v131, 0, v69
	v_max_f32_e32 v133, 0, v65
	v_max_f32_e32 v151, 0, v67
	v_pk_mul_f32 v[130:131], v[130:131], v[130:131]
	v_pk_mul_f32 v[132:133], v[132:133], v[132:133]
	v_pk_mul_f32 v[148:149], v[148:149], v[148:149]
	v_pk_mul_f32 v[150:151], v[150:151], v[150:151]
	v_cvt_pk_bf16_f32 v130, v130, v131
	v_cvt_pk_bf16_f32 v131, v148, v149
	v_cvt_pk_bf16_f32 v132, v132, v133
	v_cvt_pk_bf16_f32 v133, v150, v151
	global_store_dwordx4 v[134:135], v[130:133], off offset:256 nt
	s_nop 1
	v_max_f32_e32 v132, 0, v56
	v_max_f32_e32 v148, 0, v58
	v_max_f32_e32 v130, 0, v60
	v_max_f32_e32 v131, 0, v61
	v_max_f32_e32 v134, 0, v62
	v_max_f32_e32 v135, 0, v63
	v_max_f32_e32 v133, 0, v57
	v_pk_mul_f32 v[130:131], v[130:131], v[130:131]
	v_max_f32_e32 v149, 0, v59
	v_pk_mul_f32 v[134:135], v[134:135], v[134:135]
	s_mov_b64 s[6:7], 0x100000
	v_pk_mul_f32 v[132:133], v[132:133], v[132:133]
	v_pk_mul_f32 v[148:149], v[148:149], v[148:149]
	v_cvt_pk_bf16_f32 v130, v130, v131
	v_cvt_pk_bf16_f32 v131, v134, v135
	v_lshl_add_u64 v[134:135], v[128:129], 0, s[6:7]
	s_mov_b32 s6, 0x100000
	v_cvt_pk_bf16_f32 v132, v132, v133
	v_cvt_pk_bf16_f32 v133, v148, v149
	v_add_co_u32_e32 v148, vcc, s6, v128
	s_nop 0
	v_addc_co_u32_e32 v149, vcc, 0, v129, vcc
	global_store_dwordx4 v[148:149], v[130:133], off nt
	v_max_f32_e32 v148, 0, v54
	v_max_f32_e32 v150, 0, v50
	v_max_f32_e32 v132, 0, v48
	v_max_f32_e32 v149, 0, v55
	v_max_f32_e32 v130, 0, v52
	v_max_f32_e32 v131, 0, v53
	v_max_f32_e32 v133, 0, v49
	v_max_f32_e32 v151, 0, v51
	v_pk_mul_f32 v[130:131], v[130:131], v[130:131]
	v_pk_mul_f32 v[132:133], v[132:133], v[132:133]
	v_pk_mul_f32 v[148:149], v[148:149], v[148:149]
	v_pk_mul_f32 v[150:151], v[150:151], v[150:151]
	v_cvt_pk_bf16_f32 v130, v130, v131
	v_cvt_pk_bf16_f32 v131, v148, v149
	v_cvt_pk_bf16_f32 v132, v132, v133
	v_cvt_pk_bf16_f32 v133, v150, v151
	global_store_dwordx4 v[134:135], v[130:133], off offset:256 nt
	s_nop 1
	v_max_f32_e32 v132, 0, v40
	v_max_f32_e32 v148, 0, v42
	v_max_f32_e32 v130, 0, v44
	v_max_f32_e32 v131, 0, v45
	v_max_f32_e32 v134, 0, v46
	v_max_f32_e32 v135, 0, v47
	v_max_f32_e32 v133, 0, v41
	v_pk_mul_f32 v[130:131], v[130:131], v[130:131]
	v_max_f32_e32 v149, 0, v43
	v_pk_mul_f32 v[134:135], v[134:135], v[134:135]
	s_mov_b64 s[6:7], 0x120000
	v_pk_mul_f32 v[132:133], v[132:133], v[132:133]
	v_pk_mul_f32 v[148:149], v[148:149], v[148:149]
	v_cvt_pk_bf16_f32 v130, v130, v131
	v_cvt_pk_bf16_f32 v131, v134, v135
	v_lshl_add_u64 v[134:135], v[128:129], 0, s[6:7]
	s_mov_b32 s6, 0x120000
	v_cvt_pk_bf16_f32 v132, v132, v133
	v_cvt_pk_bf16_f32 v133, v148, v149
	v_add_co_u32_e32 v148, vcc, s6, v128
	s_nop 0
	v_addc_co_u32_e32 v149, vcc, 0, v129, vcc
	global_store_dwordx4 v[148:149], v[130:133], off nt
	v_max_f32_e32 v148, 0, v38
	v_max_f32_e32 v150, 0, v34
	v_max_f32_e32 v132, 0, v32
	v_max_f32_e32 v149, 0, v39
	v_max_f32_e32 v130, 0, v36
	v_max_f32_e32 v131, 0, v37
	v_max_f32_e32 v133, 0, v33
	v_max_f32_e32 v151, 0, v35
	v_pk_mul_f32 v[130:131], v[130:131], v[130:131]
	v_pk_mul_f32 v[132:133], v[132:133], v[132:133]
	v_pk_mul_f32 v[148:149], v[148:149], v[148:149]
	v_pk_mul_f32 v[150:151], v[150:151], v[150:151]
	v_cvt_pk_bf16_f32 v130, v130, v131
	v_cvt_pk_bf16_f32 v131, v148, v149
	v_cvt_pk_bf16_f32 v132, v132, v133
	v_cvt_pk_bf16_f32 v133, v150, v151
	global_store_dwordx4 v[134:135], v[130:133], off offset:256 nt
	s_nop 1
	v_max_f32_e32 v132, 0, v24
	v_max_f32_e32 v148, 0, v26
	v_max_f32_e32 v130, 0, v28
	v_max_f32_e32 v131, 0, v29
	v_max_f32_e32 v134, 0, v30
	v_max_f32_e32 v135, 0, v31
	v_max_f32_e32 v133, 0, v25
	v_pk_mul_f32 v[130:131], v[130:131], v[130:131]
	v_max_f32_e32 v149, 0, v27
	v_pk_mul_f32 v[134:135], v[134:135], v[134:135]
	s_mov_b64 s[6:7], 0x140000
	v_pk_mul_f32 v[132:133], v[132:133], v[132:133]
	v_pk_mul_f32 v[148:149], v[148:149], v[148:149]
	v_cvt_pk_bf16_f32 v130, v130, v131
	v_cvt_pk_bf16_f32 v131, v134, v135
	v_lshl_add_u64 v[134:135], v[128:129], 0, s[6:7]
	s_mov_b32 s6, 0x140000
	v_cvt_pk_bf16_f32 v132, v132, v133
	v_cvt_pk_bf16_f32 v133, v148, v149
	v_add_co_u32_e32 v148, vcc, s6, v128
	s_nop 0
	v_addc_co_u32_e32 v149, vcc, 0, v129, vcc
	global_store_dwordx4 v[148:149], v[130:133], off nt
	v_max_f32_e32 v148, 0, v22
	v_max_f32_e32 v150, 0, v18
	v_max_f32_e32 v132, 0, v16
	v_max_f32_e32 v149, 0, v23
	v_max_f32_e32 v130, 0, v20
	v_max_f32_e32 v131, 0, v21
	v_max_f32_e32 v133, 0, v17
	v_max_f32_e32 v151, 0, v19
	v_pk_mul_f32 v[130:131], v[130:131], v[130:131]
	v_pk_mul_f32 v[132:133], v[132:133], v[132:133]
	v_pk_mul_f32 v[148:149], v[148:149], v[148:149]
	v_pk_mul_f32 v[150:151], v[150:151], v[150:151]
	v_cvt_pk_bf16_f32 v130, v130, v131
	v_cvt_pk_bf16_f32 v131, v148, v149
	v_cvt_pk_bf16_f32 v132, v132, v133
	v_cvt_pk_bf16_f32 v133, v150, v151
	global_store_dwordx4 v[134:135], v[130:133], off offset:256 nt
	s_nop 1
	v_max_f32_e32 v132, 0, v8
	v_max_f32_e32 v148, 0, v10
	v_max_f32_e32 v130, 0, v12
	v_max_f32_e32 v131, 0, v13
	v_max_f32_e32 v134, 0, v14
	v_max_f32_e32 v135, 0, v15
	v_pk_mul_f32 v[130:131], v[130:131], v[130:131]
	v_pk_mul_f32 v[134:135], v[134:135], v[134:135]
	s_mov_b64 s[6:7], 0x160000
	v_max_f32_e32 v133, 0, v9
	v_max_f32_e32 v149, 0, v11
	v_cvt_pk_bf16_f32 v130, v130, v131
	v_cvt_pk_bf16_f32 v131, v134, v135
	v_lshl_add_u64 v[134:135], v[128:129], 0, s[6:7]
	s_mov_b32 s6, 0x160000
	v_pk_mul_f32 v[132:133], v[132:133], v[132:133]
	v_pk_mul_f32 v[148:149], v[148:149], v[148:149]
	v_add_co_u32_e32 v128, vcc, s6, v128
	v_cvt_pk_bf16_f32 v132, v132, v133
	v_cvt_pk_bf16_f32 v133, v148, v149
	v_addc_co_u32_e32 v129, vcc, 0, v129, vcc
	global_store_dwordx4 v[128:129], v[130:133], off nt
	s_nop 1
	v_max_f32_e32 v130, 0, v0
	v_max_f32_e32 v148, 0, v2
	v_max_f32_e32 v147, v3, v3
	v_max_f32_e32 v128, 0, v4
	v_max_f32_e32 v129, 0, v5
	v_max_f32_e32 v131, 0, v1
	v_max_f32_e32 v132, 0, v6
	v_max_f32_e32 v133, 0, v7
	v_max_f32_e32 v149, 0, v147
	v_pk_mul_f32 v[128:129], v[128:129], v[128:129]
	v_pk_mul_f32 v[130:131], v[130:131], v[130:131]
	v_pk_mul_f32 v[132:133], v[132:133], v[132:133]
	v_pk_mul_f32 v[148:149], v[148:149], v[148:149]
	v_cvt_pk_bf16_f32 v128, v128, v129
	v_cvt_pk_bf16_f32 v129, v132, v133
	v_cvt_pk_bf16_f32 v130, v130, v131
	v_cvt_pk_bf16_f32 v131, v148, v149
	global_store_dwordx4 v[134:135], v[128:131], off offset:256 nt
